# P8 / P10 K-loop back edge: counter, pointer updates and exit test moved in front of the iteration's closing barrier
# baseline (speedup 1.0000x reference)
; #define PG8_STAGE(bufoff, gbase, voff) do { _Pragma("unroll") for (int _i = 0; _i < 2; ++_i) \
;         __builtin_amdgcn_global_load_lds((const unsigned*)((const char*)(gbase) + (voff)[_i]), (PG8_LAS unsigned*)(lds + (bufoff) + ldsw + _i * 8192), 16, 0, 0); } while (0)
; #define PG8_LDA(dst, b, h) do { _Pragma("unroll") for (int m = 0; m < 4; ++m) _Pragma("unroll") for (int k = 0; k < 2; ++k) dst[m][k] = *(const PG8_LAS bf16x8*)(lds + PG8_SA(b, h) + aoff + m * 2048 + k * 1024); } while (0)
; #define PG8_LDB(dst, b, h) do { _Pragma("unroll") for (int n = 0; n < 2; ++n) _Pragma("unroll") for (int k = 0; k < 2; ++k) dst[n][k] = *(const PG8_LAS bf16x8*)(lds + PG8_SB(b, h) + boff + n * 2048 + k * 1024); } while (0)
; #define PG8_WAIT_V(n) asm volatile("s_waitcnt vmcnt(" #n ")" ::: "memory")
; #define PG8_WAIT_L(n) asm volatile("s_waitcnt lgkmcnt(" #n ")" ::: "memory")
; #define PG8_BAR __builtin_amdgcn_s_barrier()
; #define PG8_SCHED __builtin_amdgcn_sched_barrier(0)
; template <class Epi, class Sched, bool ALIGN_EPI = false, bool SP2 = false>
; __device__ __forceinline__ void gemm_phase(PG8_LAS unsigned char* lds, const Gemm g, const Sched& S, const Epi& E) {
;     ...
;         for (int t = 0; t < nt; t += 2) {
;             const bool last = (t == nt - 2);
;             const char* a1 = cA + (size_t)(t + 1) * kstep;
;             const char* a2 = last ? nA : cA + (size_t)(t + 2) * kstep; const char* b2 = last ? nB : cB + (size_t)(t + 2) * kstep;
;             const char* a3 = a2 + kstep; const char* b3 = b2 + kstep;
;             if (last && has_next) S.a_ready(nxt);
;             if constexpr (SP2) {
;             PG8_LDB(B0, 0, 0); PG8_LDB(B1, 0, 1); PG8_SCHED; PG8_LDA(At, 0, 0); PG8_STAGE(PG8_SA(1, 1), a1 + hstep, voffA);
;             PG8_WAIT_V(8); PG8_WAIT_L(0); PG8_BAR; PG8_MMA(0, 0, At, B0); PG8_MMA(0, 1, At, B1); PG8_BAR; PG8_SCHED;
;             PG8_LDA(At, 0, 1); PG8_STAGE(PG8_SB(0, 0), b2, voffB); PG8_STAGE(PG8_SB(0, 1), b2 + hstep, voffB); PG8_STAGE(PG8_SA(0, 0), a2, voffA);
;             PG8_WAIT_V(8); PG8_WAIT_L(0); PG8_BAR; PG8_MMA(1, 0, At, B0); PG8_MMA(1, 1, At, B1); PG8_BAR; PG8_SCHED;
.LBB0_886:
	ds_read_b128 v[140:143], v178
	ds_read_b128 v[144:147], v178 offset:1024
	ds_read_b128 v[148:151], v178 offset:2048
	ds_read_b128 v[152:155], v178 offset:3072
	ds_read_b128 v[156:159], v179
	ds_read_b128 v[160:163], v179 offset:1024
	ds_read_b128 v[164:167], v179 offset:2048
	ds_read_b128 v[168:171], v179 offset:3072
	s_add_u32 s26, s76, 0xfffc0080
	s_addc_u32 s27, s77, -1
	s_cmp_eq_u32 vcc_hi, 12
	s_cselect_b32 s81, s17, s27
	s_cselect_b32 s80, s19, s26
	s_cselect_b32 s79, s67, vcc_lo
	s_cselect_b32 s78, s69, s75
	v_lshl_add_u64 v[216:217], s[76:77], 0, v[132:133]
	s_add_i32 m0, s92, 0xc000
	ds_read_b128 v[182:185], v180
	ds_read_b128 v[186:189], v180 offset:1024
	ds_read_b128 v[190:193], v180 offset:2048
	ds_read_b128 v[196:199], v180 offset:3072
	ds_read_b128 v[200:203], v180 offset:4096
	ds_read_b128 v[204:207], v180 offset:5120
	ds_read_b128 v[208:211], v180 offset:6144
	ds_read_b128 v[212:215], v180 offset:7168
	global_load_lds_dwordx4 v[216:217], off
	v_lshl_add_u64 v[216:217], s[76:77], 0, v[134:135]
	s_add_i32 m0, s92, 0xe000
	s_nop 0
	global_load_lds_dwordx4 v[216:217], off
	s_waitcnt vmcnt(8)
	s_waitcnt lgkmcnt(0)
	s_barrier
	s_setprio 1
	s_waitcnt lgkmcnt(0)
	v_mfma_f32_16x16x32_bf16 v[124:127], v[182:185], v[140:143], v[124:127]
	v_mfma_f32_16x16x32_bf16 v[116:119], v[182:185], v[148:151], v[116:119]
	v_mfma_f32_16x16x32_bf16 v[108:111], v[190:193], v[140:143], v[108:111]
	v_mfma_f32_16x16x32_bf16 v[100:103], v[190:193], v[148:151], v[100:103]
	v_mfma_f32_16x16x32_bf16 v[92:95], v[200:203], v[140:143], v[92:95]
	v_mfma_f32_16x16x32_bf16 v[84:87], v[200:203], v[148:151], v[84:87]
	v_mfma_f32_16x16x32_bf16 v[68:71], v[208:211], v[140:143], v[68:71]
	v_mfma_f32_16x16x32_bf16 v[76:79], v[208:211], v[148:151], v[76:79]
	v_mfma_f32_16x16x32_bf16 v[124:127], v[186:189], v[144:147], v[124:127]
	v_mfma_f32_16x16x32_bf16 v[116:119], v[186:189], v[152:155], v[116:119]
	v_mfma_f32_16x16x32_bf16 v[108:111], v[196:199], v[144:147], v[108:111]
	v_mfma_f32_16x16x32_bf16 v[100:103], v[196:199], v[152:155], v[100:103]
	v_mfma_f32_16x16x32_bf16 v[92:95], v[204:207], v[144:147], v[92:95]
	v_mfma_f32_16x16x32_bf16 v[84:87], v[204:207], v[152:155], v[84:87]
	v_mfma_f32_16x16x32_bf16 v[68:71], v[212:215], v[144:147], v[68:71]
	v_mfma_f32_16x16x32_bf16 v[76:79], v[212:215], v[152:155], v[76:79]
	s_setprio 0
	s_setprio 1
	v_mfma_f32_16x16x32_bf16 v[120:123], v[182:185], v[156:159], v[120:123]
	v_mfma_f32_16x16x32_bf16 v[112:115], v[182:185], v[164:167], v[112:115]
	v_mfma_f32_16x16x32_bf16 v[104:107], v[190:193], v[156:159], v[104:107]
	v_mfma_f32_16x16x32_bf16 v[96:99], v[190:193], v[164:167], v[96:99]
	v_mfma_f32_16x16x32_bf16 v[88:91], v[200:203], v[156:159], v[88:91]
	v_mfma_f32_16x16x32_bf16 v[80:83], v[200:203], v[164:167], v[80:83]
	v_mfma_f32_16x16x32_bf16 v[64:67], v[208:211], v[156:159], v[64:67]
	v_mfma_f32_16x16x32_bf16 v[72:75], v[208:211], v[164:167], v[72:75]
	v_mfma_f32_16x16x32_bf16 v[120:123], v[186:189], v[160:163], v[120:123]
	v_mfma_f32_16x16x32_bf16 v[112:115], v[186:189], v[168:171], v[112:115]
	v_mfma_f32_16x16x32_bf16 v[104:107], v[196:199], v[160:163], v[104:107]
	v_mfma_f32_16x16x32_bf16 v[96:99], v[196:199], v[168:171], v[96:99]
	v_mfma_f32_16x16x32_bf16 v[88:91], v[204:207], v[160:163], v[88:91]
	v_mfma_f32_16x16x32_bf16 v[80:83], v[204:207], v[168:171], v[80:83]
	v_mfma_f32_16x16x32_bf16 v[64:67], v[212:215], v[160:163], v[64:67]
	v_mfma_f32_16x16x32_bf16 v[72:75], v[212:215], v[168:171], v[72:75]
	s_setprio 0
	s_barrier
	s_add_i32 s26, s33, s91
	v_lshl_add_u64 v[216:217], s[78:79], 0, v[128:129]
	s_mov_b32 m0, s26
	ds_read_b128 v[182:185], v180 offset:16384
	ds_read_b128 v[186:189], v180 offset:17408
	ds_read_b128 v[190:193], v180 offset:18432
	ds_read_b128 v[196:199], v180 offset:19456
	ds_read_b128 v[200:203], v180 offset:20480
	ds_read_b128 v[204:207], v180 offset:21504
	ds_read_b128 v[208:211], v180 offset:22528
	ds_read_b128 v[212:215], v180 offset:23552
	global_load_lds_dwordx4 v[216:217], off
	s_add_i32 m0, s26, 0x2000
	s_add_u32 s26, s78, 0x40000
	v_lshl_add_u64 v[218:219], s[78:79], 0, v[130:131]
	s_addc_u32 s27, s79, 0
	s_add_i32 s82, s36, s91
	global_load_lds_dwordx4 v[218:219], off
	v_lshl_add_u64 v[220:221], s[26:27], 0, v[128:129]
	s_mov_b32 m0, s82
	v_lshl_add_u64 v[222:223], s[80:81], 0, v[130:131]
	global_load_lds_dwordx4 v[220:221], off
	v_lshl_add_u64 v[220:221], s[26:27], 0, v[130:131]
	s_add_i32 m0, s82, 0x2000
	s_nop 0
	global_load_lds_dwordx4 v[220:221], off
	v_lshl_add_u64 v[220:221], s[80:81], 0, v[128:129]
	s_mov_b32 m0, s92
	s_nop 0
	global_load_lds_dwordx4 v[220:221], off
	s_mov_b32 m0, s93
	s_nop 0
	global_load_lds_dwordx4 v[222:223], off
	s_waitcnt vmcnt(8)
	s_waitcnt lgkmcnt(0)
	s_barrier
; #define PG8_STAGE(bufoff, gbase, voff) do { _Pragma("unroll") for (int _i = 0; _i < 2; ++_i) \
;         __builtin_amdgcn_global_load_lds((const unsigned*)((const char*)(gbase) + (voff)[_i]), (PG8_LAS unsigned*)(lds + (bufoff) + ldsw + _i * 8192), 16, 0, 0); } while (0)
; #define PG8_LDA(dst, b, h) do { _Pragma("unroll") for (int m = 0; m < 4; ++m) _Pragma("unroll") for (int k = 0; k < 2; ++k) dst[m][k] = *(const PG8_LAS bf16x8*)(lds + PG8_SA(b, h) + aoff + m * 2048 + k * 1024); } while (0)
; #define PG8_LDB(dst, b, h) do { _Pragma("unroll") for (int n = 0; n < 2; ++n) _Pragma("unroll") for (int k = 0; k < 2; ++k) dst[n][k] = *(const PG8_LAS bf16x8*)(lds + PG8_SB(b, h) + boff + n * 2048 + k * 1024); } while (0)
; #define PG8_WAIT_V(n) asm volatile("s_waitcnt vmcnt(" #n ")" ::: "memory")
; #define PG8_WAIT_L(n) asm volatile("s_waitcnt lgkmcnt(" #n ")" ::: "memory")
; #define PG8_BAR __builtin_amdgcn_s_barrier()
; #define PG8_SCHED __builtin_amdgcn_sched_barrier(0)
; template <class Epi, class Sched, bool ALIGN_EPI = false, bool SP2 = false>
; __device__ __forceinline__ void gemm_phase(PG8_LAS unsigned char* lds, const Gemm g, const Sched& S, const Epi& E) {
;     ...
;             PG8_WAIT_V(8); PG8_WAIT_L(0); PG8_BAR; PG8_MMA(1, 0, At, B0); PG8_MMA(1, 1, At, B1); PG8_BAR; PG8_SCHED;
;             PG8_LDB(B0, 1, 0); PG8_LDB(B1, 1, 1); PG8_SCHED; PG8_LDA(At, 1, 0); PG8_STAGE(PG8_SA(0, 1), a2 + hstep, voffA);
;             PG8_WAIT_V(8); PG8_WAIT_L(0); PG8_BAR; PG8_MMA(0, 0, At, B0); PG8_MMA(0, 1, At, B1); PG8_BAR; PG8_SCHED;
	s_setprio 1
	s_waitcnt lgkmcnt(0)
	v_mfma_f32_16x16x32_bf16 v[60:63], v[182:185], v[140:143], v[60:63]
	v_mfma_f32_16x16x32_bf16 v[52:55], v[182:185], v[148:151], v[52:55]
	v_mfma_f32_16x16x32_bf16 v[44:47], v[190:193], v[140:143], v[44:47]
	v_mfma_f32_16x16x32_bf16 v[36:39], v[190:193], v[148:151], v[36:39]
	v_mfma_f32_16x16x32_bf16 v[28:31], v[200:203], v[140:143], v[28:31]
	v_mfma_f32_16x16x32_bf16 v[20:23], v[200:203], v[148:151], v[20:23]
	v_mfma_f32_16x16x32_bf16 v[0:3], v[208:211], v[140:143], v[0:3]
	v_mfma_f32_16x16x32_bf16 v[12:15], v[208:211], v[148:151], v[12:15]
	v_mfma_f32_16x16x32_bf16 v[60:63], v[186:189], v[144:147], v[60:63]
	v_mfma_f32_16x16x32_bf16 v[52:55], v[186:189], v[152:155], v[52:55]
	v_mfma_f32_16x16x32_bf16 v[44:47], v[196:199], v[144:147], v[44:47]
	v_mfma_f32_16x16x32_bf16 v[36:39], v[196:199], v[152:155], v[36:39]
	v_mfma_f32_16x16x32_bf16 v[28:31], v[204:207], v[144:147], v[28:31]
	v_mfma_f32_16x16x32_bf16 v[20:23], v[204:207], v[152:155], v[20:23]
	v_mfma_f32_16x16x32_bf16 v[0:3], v[212:215], v[144:147], v[0:3]
	v_mfma_f32_16x16x32_bf16 v[12:15], v[212:215], v[152:155], v[12:15]
	s_setprio 0
	s_setprio 1
	v_mfma_f32_16x16x32_bf16 v[56:59], v[182:185], v[156:159], v[56:59]
	v_mfma_f32_16x16x32_bf16 v[48:51], v[182:185], v[164:167], v[48:51]
	v_mfma_f32_16x16x32_bf16 v[40:43], v[190:193], v[156:159], v[40:43]
	v_mfma_f32_16x16x32_bf16 v[32:35], v[190:193], v[164:167], v[32:35]
	v_mfma_f32_16x16x32_bf16 v[24:27], v[200:203], v[156:159], v[24:27]
	v_mfma_f32_16x16x32_bf16 v[16:19], v[200:203], v[164:167], v[16:19]
	v_mfma_f32_16x16x32_bf16 v[4:7], v[208:211], v[156:159], v[4:7]
	v_mfma_f32_16x16x32_bf16 v[8:11], v[208:211], v[164:167], v[8:11]
	v_mfma_f32_16x16x32_bf16 v[56:59], v[186:189], v[160:163], v[56:59]
	v_mfma_f32_16x16x32_bf16 v[48:51], v[186:189], v[168:171], v[48:51]
	v_mfma_f32_16x16x32_bf16 v[40:43], v[196:199], v[160:163], v[40:43]
	v_mfma_f32_16x16x32_bf16 v[32:35], v[196:199], v[168:171], v[32:35]
	v_mfma_f32_16x16x32_bf16 v[24:27], v[204:207], v[160:163], v[24:27]
	v_mfma_f32_16x16x32_bf16 v[16:19], v[204:207], v[168:171], v[16:19]
	v_mfma_f32_16x16x32_bf16 v[4:7], v[212:215], v[160:163], v[4:7]
	v_mfma_f32_16x16x32_bf16 v[8:11], v[212:215], v[168:171], v[8:11]
	s_setprio 0
	s_barrier
	s_add_i32 s82, 0, 0x18000
	s_add_i32 s24, 0, 0x1c000
	v_add_u32_e32 v152, s82, v173
	v_add_u32_e32 v168, s24, v173
	ds_read_b128 v[140:143], v152
	ds_read_b128 v[144:147], v152 offset:1024
	ds_read_b128 v[148:151], v152 offset:2048
	ds_read_b128 v[152:155], v152 offset:3072
	ds_read_b128 v[156:159], v168
	ds_read_b128 v[160:163], v168 offset:1024
	ds_read_b128 v[164:167], v168 offset:2048
	ds_read_b128 v[168:171], v168 offset:3072
	s_add_u32 s26, s80, 0x40000
	s_addc_u32 s27, s81, 0
	s_mov_b32 m0, s94
	v_lshl_add_u64 v[224:225], s[26:27], 0, v[128:129]
	ds_read_b128 v[182:185], v180 offset:32768
	ds_read_b128 v[186:189], v180 offset:33792
	ds_read_b128 v[190:193], v180 offset:34816
	ds_read_b128 v[196:199], v180 offset:35840
	ds_read_b128 v[200:203], v180 offset:36864
	ds_read_b128 v[204:207], v180 offset:37888
	ds_read_b128 v[208:211], v180 offset:38912
	ds_read_b128 v[212:215], v180 offset:39936
	global_load_lds_dwordx4 v[224:225], off
	v_lshl_add_u64 v[224:225], s[26:27], 0, v[130:131]
	s_mov_b32 m0, s95
	s_nop 0
	global_load_lds_dwordx4 v[224:225], off
	s_waitcnt vmcnt(8)
	s_waitcnt lgkmcnt(0)
	s_barrier
	s_setprio 1
	s_waitcnt lgkmcnt(0)
	v_mfma_f32_16x16x32_bf16 v[124:127], v[182:185], v[140:143], v[124:127]
	v_mfma_f32_16x16x32_bf16 v[116:119], v[182:185], v[148:151], v[116:119]
	v_mfma_f32_16x16x32_bf16 v[108:111], v[190:193], v[140:143], v[108:111]
	v_mfma_f32_16x16x32_bf16 v[100:103], v[190:193], v[148:151], v[100:103]
	v_mfma_f32_16x16x32_bf16 v[92:95], v[200:203], v[140:143], v[92:95]
	v_mfma_f32_16x16x32_bf16 v[84:87], v[200:203], v[148:151], v[84:87]
	v_mfma_f32_16x16x32_bf16 v[68:71], v[208:211], v[140:143], v[68:71]
	v_mfma_f32_16x16x32_bf16 v[76:79], v[208:211], v[148:151], v[76:79]
	v_mfma_f32_16x16x32_bf16 v[124:127], v[186:189], v[144:147], v[124:127]
	v_mfma_f32_16x16x32_bf16 v[116:119], v[186:189], v[152:155], v[116:119]
	v_mfma_f32_16x16x32_bf16 v[108:111], v[196:199], v[144:147], v[108:111]
	v_mfma_f32_16x16x32_bf16 v[100:103], v[196:199], v[152:155], v[100:103]
	v_mfma_f32_16x16x32_bf16 v[92:95], v[204:207], v[144:147], v[92:95]
	v_mfma_f32_16x16x32_bf16 v[84:87], v[204:207], v[152:155], v[84:87]
	v_mfma_f32_16x16x32_bf16 v[68:71], v[212:215], v[144:147], v[68:71]
	v_mfma_f32_16x16x32_bf16 v[76:79], v[212:215], v[152:155], v[76:79]
	s_setprio 0
	s_setprio 1
	v_mfma_f32_16x16x32_bf16 v[120:123], v[182:185], v[156:159], v[120:123]
	v_mfma_f32_16x16x32_bf16 v[112:115], v[182:185], v[164:167], v[112:115]
	v_mfma_f32_16x16x32_bf16 v[104:107], v[190:193], v[156:159], v[104:107]
	v_mfma_f32_16x16x32_bf16 v[96:99], v[190:193], v[164:167], v[96:99]
	v_mfma_f32_16x16x32_bf16 v[88:91], v[200:203], v[156:159], v[88:91]
	v_mfma_f32_16x16x32_bf16 v[80:83], v[200:203], v[164:167], v[80:83]
	v_mfma_f32_16x16x32_bf16 v[64:67], v[208:211], v[156:159], v[64:67]
	v_mfma_f32_16x16x32_bf16 v[72:75], v[208:211], v[164:167], v[72:75]
	v_mfma_f32_16x16x32_bf16 v[120:123], v[186:189], v[160:163], v[120:123]
	v_mfma_f32_16x16x32_bf16 v[112:115], v[186:189], v[168:171], v[112:115]
	v_mfma_f32_16x16x32_bf16 v[104:107], v[196:199], v[160:163], v[104:107]
	v_mfma_f32_16x16x32_bf16 v[96:99], v[196:199], v[168:171], v[96:99]
	v_mfma_f32_16x16x32_bf16 v[88:91], v[204:207], v[160:163], v[88:91]
	v_mfma_f32_16x16x32_bf16 v[80:83], v[204:207], v[168:171], v[80:83]
	v_mfma_f32_16x16x32_bf16 v[64:67], v[212:215], v[160:163], v[64:67]
	v_mfma_f32_16x16x32_bf16 v[72:75], v[212:215], v[168:171], v[72:75]
	s_setprio 0
	s_barrier
; #define PG8_STAGE(bufoff, gbase, voff) do { _Pragma("unroll") for (int _i = 0; _i < 2; ++_i) \
;         __builtin_amdgcn_global_load_lds((const unsigned*)((const char*)(gbase) + (voff)[_i]), (PG8_LAS unsigned*)(lds + (bufoff) + ldsw + _i * 8192), 16, 0, 0); } while (0)
; #define PG8_LDA(dst, b, h) do { _Pragma("unroll") for (int m = 0; m < 4; ++m) _Pragma("unroll") for (int k = 0; k < 2; ++k) dst[m][k] = *(const PG8_LAS bf16x8*)(lds + PG8_SA(b, h) + aoff + m * 2048 + k * 1024); } while (0)
; #define PG8_WAIT_V(n) asm volatile("s_waitcnt vmcnt(" #n ")" ::: "memory")
; #define PG8_WAIT_L(n) asm volatile("s_waitcnt lgkmcnt(" #n ")" ::: "memory")
; #define PG8_BAR __builtin_amdgcn_s_barrier()
; #define PG8_SCHED __builtin_amdgcn_sched_barrier(0)
; template <class Epi, class Sched, bool ALIGN_EPI = false, bool SP2 = false>
; __device__ __forceinline__ void gemm_phase(PG8_LAS unsigned char* lds, const Gemm g, const Sched& S, const Epi& E) {
;     ...
;         for (int t = 0; t < nt; t += 2) {
;     ...
;             PG8_LDA(At, 1, 1); PG8_STAGE(PG8_SB(1, 0), b3, voffB); PG8_STAGE(PG8_SB(1, 1), b3 + hstep, voffB); PG8_STAGE(PG8_SA(1, 0), a3, voffA);
;             PG8_WAIT_V(8); PG8_WAIT_L(0); PG8_BAR; PG8_MMA(1, 0, At, B0); PG8_MMA(1, 1, At, B1); PG8_BAR; PG8_SCHED;
	s_add_i32 s25, s82, s91
	v_lshl_add_u64 v[216:217], v[216:217], 0, s[54:55]
	s_mov_b32 m0, s25
	ds_read_b128 v[182:185], v180 offset:49152
	ds_read_b128 v[186:189], v180 offset:50176
	ds_read_b128 v[190:193], v180 offset:51200
	ds_read_b128 v[196:199], v180 offset:52224
	ds_read_b128 v[200:203], v180 offset:53248
	ds_read_b128 v[204:207], v180 offset:54272
	ds_read_b128 v[208:211], v180 offset:55296
	ds_read_b128 v[212:215], v180 offset:56320
	global_load_lds_dwordx4 v[216:217], off
	s_add_i32 m0, s25, 0x2000
	s_add_u32 s26, s78, 0x40080
	v_lshl_add_u64 v[216:217], v[218:219], 0, s[54:55]
	s_addc_u32 s27, s79, 0
	s_add_i32 s24, s24, s91
	global_load_lds_dwordx4 v[216:217], off
	v_lshl_add_u64 v[216:217], s[26:27], 0, v[128:129]
	s_mov_b32 m0, s24
	s_nop 0
	global_load_lds_dwordx4 v[216:217], off
	v_lshl_add_u64 v[216:217], s[26:27], 0, v[130:131]
	s_add_i32 m0, s24, 0x2000
	s_nop 0
	global_load_lds_dwordx4 v[216:217], off
	v_lshl_add_u64 v[216:217], v[220:221], 0, s[54:55]
	s_mov_b32 m0, s86
	s_nop 0
	global_load_lds_dwordx4 v[216:217], off
	v_lshl_add_u64 v[216:217], v[222:223], 0, s[54:55]
	s_mov_b32 m0, s83
	s_nop 0
	global_load_lds_dwordx4 v[216:217], off
	s_waitcnt vmcnt(8)
	s_waitcnt lgkmcnt(0)
	s_barrier
	s_setprio 1
	s_waitcnt lgkmcnt(0)
	v_mfma_f32_16x16x32_bf16 v[60:63], v[182:185], v[140:143], v[60:63]
	v_mfma_f32_16x16x32_bf16 v[52:55], v[182:185], v[148:151], v[52:55]
	v_mfma_f32_16x16x32_bf16 v[44:47], v[190:193], v[140:143], v[44:47]
	v_mfma_f32_16x16x32_bf16 v[36:39], v[190:193], v[148:151], v[36:39]
	v_mfma_f32_16x16x32_bf16 v[28:31], v[200:203], v[140:143], v[28:31]
	v_mfma_f32_16x16x32_bf16 v[20:23], v[200:203], v[148:151], v[20:23]
	v_mfma_f32_16x16x32_bf16 v[0:3], v[208:211], v[140:143], v[0:3]
	v_mfma_f32_16x16x32_bf16 v[12:15], v[208:211], v[148:151], v[12:15]
	v_mfma_f32_16x16x32_bf16 v[60:63], v[186:189], v[144:147], v[60:63]
	v_mfma_f32_16x16x32_bf16 v[52:55], v[186:189], v[152:155], v[52:55]
	v_mfma_f32_16x16x32_bf16 v[44:47], v[196:199], v[144:147], v[44:47]
	v_mfma_f32_16x16x32_bf16 v[36:39], v[196:199], v[152:155], v[36:39]
	v_mfma_f32_16x16x32_bf16 v[28:31], v[204:207], v[144:147], v[28:31]
	v_mfma_f32_16x16x32_bf16 v[20:23], v[204:207], v[152:155], v[20:23]
	v_mfma_f32_16x16x32_bf16 v[0:3], v[212:215], v[144:147], v[0:3]
	v_mfma_f32_16x16x32_bf16 v[12:15], v[212:215], v[152:155], v[12:15]
	s_setprio 0
	s_setprio 1
	v_mfma_f32_16x16x32_bf16 v[56:59], v[182:185], v[156:159], v[56:59]
	v_mfma_f32_16x16x32_bf16 v[48:51], v[182:185], v[164:167], v[48:51]
	v_mfma_f32_16x16x32_bf16 v[40:43], v[190:193], v[156:159], v[40:43]
	v_mfma_f32_16x16x32_bf16 v[32:35], v[190:193], v[164:167], v[32:35]
	v_mfma_f32_16x16x32_bf16 v[24:27], v[200:203], v[156:159], v[24:27]
	v_mfma_f32_16x16x32_bf16 v[16:19], v[200:203], v[164:167], v[16:19]
	v_mfma_f32_16x16x32_bf16 v[4:7], v[208:211], v[156:159], v[4:7]
	v_mfma_f32_16x16x32_bf16 v[8:11], v[208:211], v[164:167], v[8:11]
	v_mfma_f32_16x16x32_bf16 v[56:59], v[186:189], v[160:163], v[56:59]
	v_mfma_f32_16x16x32_bf16 v[48:51], v[186:189], v[168:171], v[48:51]
	v_mfma_f32_16x16x32_bf16 v[40:43], v[196:199], v[160:163], v[40:43]
	v_mfma_f32_16x16x32_bf16 v[32:35], v[196:199], v[168:171], v[32:35]
	v_mfma_f32_16x16x32_bf16 v[24:27], v[204:207], v[160:163], v[24:27]
	v_mfma_f32_16x16x32_bf16 v[16:19], v[204:207], v[168:171], v[16:19]
	v_mfma_f32_16x16x32_bf16 v[4:7], v[212:215], v[160:163], v[4:7]
	v_mfma_f32_16x16x32_bf16 v[8:11], v[212:215], v[168:171], v[8:11]
	s_setprio 0
	s_add_i32 vcc_hi, vcc_hi, 2
	s_add_u32 s76, s76, 0x100
	s_addc_u32 s77, s77, 0
	s_add_u32 s75, s75, 0x100
	s_addc_u32 vcc_lo, vcc_lo, 0
	s_cmp_gt_u32 vcc_hi, 13
	s_barrier
	s_cbranch_scc0 .LBB0_886
	s_and_b64 vcc, exec, s[56:57]
	s_cbranch_vccz .LBB0_889
	s_barrier

; #define PG8_STAGE(bufoff, gbase, voff) do { _Pragma("unroll") for (int _i = 0; _i < 2; ++_i) \
;         __builtin_amdgcn_global_load_lds((const unsigned*)((const char*)(gbase) + (voff)[_i]), (PG8_LAS unsigned*)(lds + (bufoff) + ldsw + _i * 8192), 16, 0, 0); } while (0)
; #define PG8_LDA(dst, b, h) do { _Pragma("unroll") for (int m = 0; m < 4; ++m) _Pragma("unroll") for (int k = 0; k < 2; ++k) dst[m][k] = *(const PG8_LAS bf16x8*)(lds + PG8_SA(b, h) + aoff + m * 2048 + k * 1024); } while (0)
; #define PG8_LDB(dst, b, h) do { _Pragma("unroll") for (int n = 0; n < 2; ++n) _Pragma("unroll") for (int k = 0; k < 2; ++k) dst[n][k] = *(const PG8_LAS bf16x8*)(lds + PG8_SB(b, h) + boff + n * 2048 + k * 1024); } while (0)
; #define PG8_WAIT_V(n) asm volatile("s_waitcnt vmcnt(" #n ")" ::: "memory")
; #define PG8_WAIT_L(n) asm volatile("s_waitcnt lgkmcnt(" #n ")" ::: "memory")
; #define PG8_BAR __builtin_amdgcn_s_barrier()
; #define PG8_SCHED __builtin_amdgcn_sched_barrier(0)
; template <class Epi, class Sched, bool ALIGN_EPI = false, bool SP2 = false>
; __device__ __forceinline__ void gemm_phase(PG8_LAS unsigned char* lds, const Gemm g, const Sched& S, const Epi& E) {
;     ...
;         for (int t = 0; t < nt; t += 2) {
;             const bool last = (t == nt - 2);
;             const char* a1 = cA + (size_t)(t + 1) * kstep;
;             const char* a2 = last ? nA : cA + (size_t)(t + 2) * kstep; const char* b2 = last ? nB : cB + (size_t)(t + 2) * kstep;
;             const char* a3 = a2 + kstep; const char* b3 = b2 + kstep;
;             if (last && has_next) S.a_ready(nxt);
;             if constexpr (SP2) {
;             PG8_LDB(B0, 0, 0); PG8_LDB(B1, 0, 1); PG8_SCHED; PG8_LDA(At, 0, 0); PG8_STAGE(PG8_SA(1, 1), a1 + hstep, voffA);
;             PG8_WAIT_V(8); PG8_WAIT_L(0); PG8_BAR; PG8_MMA(0, 0, At, B0); PG8_MMA(0, 1, At, B1); PG8_BAR; PG8_SCHED;
;             PG8_LDA(At, 0, 1); PG8_STAGE(PG8_SB(0, 0), b2, voffB); PG8_STAGE(PG8_SB(0, 1), b2 + hstep, voffB); PG8_STAGE(PG8_SA(0, 0), a2, voffA);
;             PG8_WAIT_V(8); PG8_WAIT_L(0); PG8_BAR; PG8_MMA(1, 0, At, B0); PG8_MMA(1, 1, At, B1); PG8_BAR; PG8_SCHED;
.LBB0_1134:
	s_add_u32 s36, s26, s34
	s_addc_u32 s37, s27, s35
	s_add_u32 s36, s36, 0x100
	s_addc_u32 s37, s37, 0
	s_add_u32 s71, s29, s34
	s_addc_u32 s72, s69, s35
	s_add_i32 s73, 0, 0x10000
	s_cmpk_eq_i32 s34, 0x1500
	s_cselect_b32 s39, s31, s37
	s_cselect_b32 s38, s30, s36
	v_add_u32_e32 v142, s73, v140
	s_cselect_b32 s37, s9, s72
	s_cselect_b32 s36, s8, s71
	s_add_i32 s71, 0, 0x14000
	ds_read_b128 v[150:153], v142
	ds_read_b128 v[158:161], v142 offset:1024
	ds_read_b128 v[162:165], v142 offset:2048
	ds_read_b128 v[166:169], v142 offset:3072
	v_add_u32_e32 v142, s71, v140
	ds_read_b128 v[170:173], v142
	ds_read_b128 v[174:177], v142 offset:1024
	ds_read_b128 v[178:181], v142 offset:2048
	ds_read_b128 v[182:185], v142 offset:3072
	v_lshl_add_u64 v[142:143], v[134:135], 0, s[34:35]
	s_add_i32 m0, s60, 0xc000
	ds_read_b128 v[186:189], v141
	ds_read_b128 v[190:193], v141 offset:1024
	ds_read_b128 v[196:199], v141 offset:2048
	ds_read_b128 v[200:203], v141 offset:3072
	ds_read_b128 v[204:207], v141 offset:4096
	ds_read_b128 v[208:211], v141 offset:5120
	ds_read_b128 v[212:215], v141 offset:6144
	ds_read_b128 v[216:219], v141 offset:7168
	global_load_lds_dwordx4 v[142:143], off
	v_lshl_add_u64 v[142:143], v[136:137], 0, s[34:35]
	s_add_i32 m0, s60, 0xe000
	s_nop 0
	global_load_lds_dwordx4 v[142:143], off
	s_waitcnt vmcnt(8)
	s_waitcnt lgkmcnt(0)
	s_barrier
	s_setprio 1
	s_waitcnt lgkmcnt(0)
	v_mfma_f32_16x16x32_bf16 v[124:127], v[150:153], v[186:189], v[124:127]
	v_mfma_f32_16x16x32_bf16 v[120:123], v[162:165], v[186:189], v[120:123]
	v_mfma_f32_16x16x32_bf16 v[116:119], v[150:153], v[196:199], v[116:119]
	v_mfma_f32_16x16x32_bf16 v[112:115], v[162:165], v[196:199], v[112:115]
	v_mfma_f32_16x16x32_bf16 v[92:95], v[150:153], v[204:207], v[92:95]
	v_mfma_f32_16x16x32_bf16 v[88:91], v[162:165], v[204:207], v[88:91]
	v_mfma_f32_16x16x32_bf16 v[84:87], v[150:153], v[212:215], v[84:87]
	v_mfma_f32_16x16x32_bf16 v[80:83], v[162:165], v[212:215], v[80:83]
	v_mfma_f32_16x16x32_bf16 v[124:127], v[158:161], v[190:193], v[124:127]
	v_mfma_f32_16x16x32_bf16 v[120:123], v[166:169], v[190:193], v[120:123]
	v_mfma_f32_16x16x32_bf16 v[116:119], v[158:161], v[200:203], v[116:119]
	v_mfma_f32_16x16x32_bf16 v[112:115], v[166:169], v[200:203], v[112:115]
	v_mfma_f32_16x16x32_bf16 v[92:95], v[158:161], v[208:211], v[92:95]
	v_mfma_f32_16x16x32_bf16 v[88:91], v[166:169], v[208:211], v[88:91]
	v_mfma_f32_16x16x32_bf16 v[84:87], v[158:161], v[216:219], v[84:87]
	v_mfma_f32_16x16x32_bf16 v[80:83], v[166:169], v[216:219], v[80:83]
	s_setprio 0
	s_setprio 1
	v_mfma_f32_16x16x32_bf16 v[108:111], v[170:173], v[186:189], v[108:111]
	v_mfma_f32_16x16x32_bf16 v[104:107], v[178:181], v[186:189], v[104:107]
	v_mfma_f32_16x16x32_bf16 v[100:103], v[170:173], v[196:199], v[100:103]
	v_mfma_f32_16x16x32_bf16 v[96:99], v[178:181], v[196:199], v[96:99]
	v_mfma_f32_16x16x32_bf16 v[76:79], v[170:173], v[204:207], v[76:79]
	v_mfma_f32_16x16x32_bf16 v[72:75], v[178:181], v[204:207], v[72:75]
	v_mfma_f32_16x16x32_bf16 v[68:71], v[170:173], v[212:215], v[68:71]
	v_mfma_f32_16x16x32_bf16 v[64:67], v[178:181], v[212:215], v[64:67]
	v_mfma_f32_16x16x32_bf16 v[108:111], v[174:177], v[190:193], v[108:111]
	v_mfma_f32_16x16x32_bf16 v[104:107], v[182:185], v[190:193], v[104:107]
	v_mfma_f32_16x16x32_bf16 v[100:103], v[174:177], v[200:203], v[100:103]
	v_mfma_f32_16x16x32_bf16 v[96:99], v[182:185], v[200:203], v[96:99]
	v_mfma_f32_16x16x32_bf16 v[76:79], v[174:177], v[208:211], v[76:79]
	v_mfma_f32_16x16x32_bf16 v[72:75], v[182:185], v[208:211], v[72:75]
	v_mfma_f32_16x16x32_bf16 v[68:71], v[174:177], v[216:219], v[68:71]
	v_mfma_f32_16x16x32_bf16 v[64:67], v[182:185], v[216:219], v[64:67]
	s_setprio 0
	s_barrier
	s_add_i32 s72, s73, s55
	v_lshl_add_u64 v[142:143], s[36:37], 0, v[144:145]
	s_mov_b32 m0, s72
	ds_read_b128 v[186:189], v141 offset:16384
	ds_read_b128 v[190:193], v141 offset:17408
	ds_read_b128 v[196:199], v141 offset:18432
	ds_read_b128 v[200:203], v141 offset:19456
	ds_read_b128 v[204:207], v141 offset:20480
	ds_read_b128 v[208:211], v141 offset:21504
	ds_read_b128 v[212:215], v141 offset:22528
	ds_read_b128 v[216:219], v141 offset:23552
	global_load_lds_dwordx4 v[142:143], off
	s_add_i32 m0, s72, 0x2000
	s_add_u32 s72, s36, 0xb0000
	v_lshl_add_u64 v[220:221], s[36:37], 0, v[128:129]
	s_addc_u32 s73, s37, 0
	s_add_i32 s71, s71, s55
	global_load_lds_dwordx4 v[220:221], off
	v_lshl_add_u64 v[222:223], s[72:73], 0, v[144:145]
	s_mov_b32 m0, s71
	v_lshl_add_u64 v[224:225], s[38:39], 0, v[128:129]
	global_load_lds_dwordx4 v[222:223], off
	v_lshl_add_u64 v[222:223], s[72:73], 0, v[128:129]
	s_add_i32 m0, s71, 0x2000
	s_nop 0
	global_load_lds_dwordx4 v[222:223], off
	v_lshl_add_u64 v[222:223], s[38:39], 0, v[144:145]
	s_mov_b32 m0, s60
	s_nop 0
	global_load_lds_dwordx4 v[222:223], off
	s_mov_b32 m0, s61
	s_nop 0
	global_load_lds_dwordx4 v[224:225], off
	s_waitcnt vmcnt(8)
	s_waitcnt lgkmcnt(0)
	s_barrier
; #define PG8_STAGE(bufoff, gbase, voff) do { _Pragma("unroll") for (int _i = 0; _i < 2; ++_i) \
;         __builtin_amdgcn_global_load_lds((const unsigned*)((const char*)(gbase) + (voff)[_i]), (PG8_LAS unsigned*)(lds + (bufoff) + ldsw + _i * 8192), 16, 0, 0); } while (0)
; #define PG8_LDA(dst, b, h) do { _Pragma("unroll") for (int m = 0; m < 4; ++m) _Pragma("unroll") for (int k = 0; k < 2; ++k) dst[m][k] = *(const PG8_LAS bf16x8*)(lds + PG8_SA(b, h) + aoff + m * 2048 + k * 1024); } while (0)
; #define PG8_LDB(dst, b, h) do { _Pragma("unroll") for (int n = 0; n < 2; ++n) _Pragma("unroll") for (int k = 0; k < 2; ++k) dst[n][k] = *(const PG8_LAS bf16x8*)(lds + PG8_SB(b, h) + boff + n * 2048 + k * 1024); } while (0)
; #define PG8_WAIT_V(n) asm volatile("s_waitcnt vmcnt(" #n ")" ::: "memory")
; #define PG8_WAIT_L(n) asm volatile("s_waitcnt lgkmcnt(" #n ")" ::: "memory")
; #define PG8_BAR __builtin_amdgcn_s_barrier()
; #define PG8_SCHED __builtin_amdgcn_sched_barrier(0)
; template <class Epi, class Sched, bool ALIGN_EPI = false, bool SP2 = false>
; __device__ __forceinline__ void gemm_phase(PG8_LAS unsigned char* lds, const Gemm g, const Sched& S, const Epi& E) {
;     ...
;             PG8_WAIT_V(8); PG8_WAIT_L(0); PG8_BAR; PG8_MMA(1, 0, At, B0); PG8_MMA(1, 1, At, B1); PG8_BAR; PG8_SCHED;
;             PG8_LDB(B0, 1, 0); PG8_LDB(B1, 1, 1); PG8_SCHED; PG8_LDA(At, 1, 0); PG8_STAGE(PG8_SA(0, 1), a2 + hstep, voffA);
;             PG8_WAIT_V(8); PG8_WAIT_L(0); PG8_BAR; PG8_MMA(0, 0, At, B0); PG8_MMA(0, 1, At, B1); PG8_BAR; PG8_SCHED;
	s_setprio 1
	s_waitcnt lgkmcnt(0)
	v_mfma_f32_16x16x32_bf16 v[60:63], v[150:153], v[186:189], v[60:63]
	v_mfma_f32_16x16x32_bf16 v[56:59], v[162:165], v[186:189], v[56:59]
	v_mfma_f32_16x16x32_bf16 v[52:55], v[150:153], v[196:199], v[52:55]
	v_mfma_f32_16x16x32_bf16 v[48:51], v[162:165], v[196:199], v[48:51]
	v_mfma_f32_16x16x32_bf16 v[28:31], v[150:153], v[204:207], v[28:31]
	v_mfma_f32_16x16x32_bf16 v[24:27], v[162:165], v[204:207], v[24:27]
	v_mfma_f32_16x16x32_bf16 v[20:23], v[150:153], v[212:215], v[20:23]
	v_mfma_f32_16x16x32_bf16 v[16:19], v[162:165], v[212:215], v[16:19]
	v_mfma_f32_16x16x32_bf16 v[60:63], v[158:161], v[190:193], v[60:63]
	v_mfma_f32_16x16x32_bf16 v[56:59], v[166:169], v[190:193], v[56:59]
	v_mfma_f32_16x16x32_bf16 v[52:55], v[158:161], v[200:203], v[52:55]
	v_mfma_f32_16x16x32_bf16 v[48:51], v[166:169], v[200:203], v[48:51]
	v_mfma_f32_16x16x32_bf16 v[28:31], v[158:161], v[208:211], v[28:31]
	v_mfma_f32_16x16x32_bf16 v[24:27], v[166:169], v[208:211], v[24:27]
	v_mfma_f32_16x16x32_bf16 v[20:23], v[158:161], v[216:219], v[20:23]
	v_mfma_f32_16x16x32_bf16 v[16:19], v[166:169], v[216:219], v[16:19]
	s_setprio 0
	s_setprio 1
	v_mfma_f32_16x16x32_bf16 v[44:47], v[170:173], v[186:189], v[44:47]
	v_mfma_f32_16x16x32_bf16 v[40:43], v[178:181], v[186:189], v[40:43]
	v_mfma_f32_16x16x32_bf16 v[36:39], v[170:173], v[196:199], v[36:39]
	v_mfma_f32_16x16x32_bf16 v[32:35], v[178:181], v[196:199], v[32:35]
	v_mfma_f32_16x16x32_bf16 v[12:15], v[170:173], v[204:207], v[12:15]
	v_mfma_f32_16x16x32_bf16 v[8:11], v[178:181], v[204:207], v[8:11]
	v_mfma_f32_16x16x32_bf16 v[4:7], v[170:173], v[212:215], v[4:7]
	v_mfma_f32_16x16x32_bf16 v[0:3], v[178:181], v[212:215], v[0:3]
	v_mfma_f32_16x16x32_bf16 v[44:47], v[174:177], v[190:193], v[44:47]
	v_mfma_f32_16x16x32_bf16 v[40:43], v[182:185], v[190:193], v[40:43]
	v_mfma_f32_16x16x32_bf16 v[36:39], v[174:177], v[200:203], v[36:39]
	v_mfma_f32_16x16x32_bf16 v[32:35], v[182:185], v[200:203], v[32:35]
	v_mfma_f32_16x16x32_bf16 v[12:15], v[174:177], v[208:211], v[12:15]
	v_mfma_f32_16x16x32_bf16 v[8:11], v[182:185], v[208:211], v[8:11]
	v_mfma_f32_16x16x32_bf16 v[4:7], v[174:177], v[216:219], v[4:7]
	v_mfma_f32_16x16x32_bf16 v[0:3], v[182:185], v[216:219], v[0:3]
	s_setprio 0
	s_barrier
	s_add_i32 s71, 0, 0x18000
	s_add_i32 s72, 0, 0x1c000
	v_add_u32_e32 v166, s71, v140
	v_add_u32_e32 v182, s72, v140
	ds_read_b128 v[150:153], v166
	ds_read_b128 v[158:161], v166 offset:1024
	ds_read_b128 v[162:165], v166 offset:2048
	ds_read_b128 v[166:169], v166 offset:3072
	ds_read_b128 v[170:173], v182
	ds_read_b128 v[174:177], v182 offset:1024
	ds_read_b128 v[178:181], v182 offset:2048
	ds_read_b128 v[182:185], v182 offset:3072
	s_add_u32 s38, s38, 0xb0000
	s_addc_u32 s39, s39, 0
	s_mov_b32 m0, s62
	v_lshl_add_u64 v[226:227], s[38:39], 0, v[144:145]
	ds_read_b128 v[186:189], v141 offset:32768
	ds_read_b128 v[190:193], v141 offset:33792
	ds_read_b128 v[196:199], v141 offset:34816
	ds_read_b128 v[200:203], v141 offset:35840
	ds_read_b128 v[204:207], v141 offset:36864
	ds_read_b128 v[208:211], v141 offset:37888
	ds_read_b128 v[212:215], v141 offset:38912
	ds_read_b128 v[216:219], v141 offset:39936
	global_load_lds_dwordx4 v[226:227], off
	v_lshl_add_u64 v[226:227], s[38:39], 0, v[128:129]
	s_mov_b32 m0, s63
	s_nop 0
	global_load_lds_dwordx4 v[226:227], off
	s_waitcnt vmcnt(8)
	s_waitcnt lgkmcnt(0)
	s_barrier
	s_setprio 1
	s_waitcnt lgkmcnt(0)
	v_mfma_f32_16x16x32_bf16 v[124:127], v[150:153], v[186:189], v[124:127]
	v_mfma_f32_16x16x32_bf16 v[120:123], v[162:165], v[186:189], v[120:123]
	v_mfma_f32_16x16x32_bf16 v[116:119], v[150:153], v[196:199], v[116:119]
	v_mfma_f32_16x16x32_bf16 v[112:115], v[162:165], v[196:199], v[112:115]
	v_mfma_f32_16x16x32_bf16 v[92:95], v[150:153], v[204:207], v[92:95]
	v_mfma_f32_16x16x32_bf16 v[88:91], v[162:165], v[204:207], v[88:91]
	v_mfma_f32_16x16x32_bf16 v[84:87], v[150:153], v[212:215], v[84:87]
	v_mfma_f32_16x16x32_bf16 v[80:83], v[162:165], v[212:215], v[80:83]
	v_mfma_f32_16x16x32_bf16 v[124:127], v[158:161], v[190:193], v[124:127]
	v_mfma_f32_16x16x32_bf16 v[120:123], v[166:169], v[190:193], v[120:123]
	v_mfma_f32_16x16x32_bf16 v[116:119], v[158:161], v[200:203], v[116:119]
	v_mfma_f32_16x16x32_bf16 v[112:115], v[166:169], v[200:203], v[112:115]
	v_mfma_f32_16x16x32_bf16 v[92:95], v[158:161], v[208:211], v[92:95]
	v_mfma_f32_16x16x32_bf16 v[88:91], v[166:169], v[208:211], v[88:91]
	v_mfma_f32_16x16x32_bf16 v[84:87], v[158:161], v[216:219], v[84:87]
	v_mfma_f32_16x16x32_bf16 v[80:83], v[166:169], v[216:219], v[80:83]
	s_setprio 0
	s_setprio 1
	v_mfma_f32_16x16x32_bf16 v[108:111], v[170:173], v[186:189], v[108:111]
	v_mfma_f32_16x16x32_bf16 v[104:107], v[178:181], v[186:189], v[104:107]
	v_mfma_f32_16x16x32_bf16 v[100:103], v[170:173], v[196:199], v[100:103]
	v_mfma_f32_16x16x32_bf16 v[96:99], v[178:181], v[196:199], v[96:99]
	v_mfma_f32_16x16x32_bf16 v[76:79], v[170:173], v[204:207], v[76:79]
	v_mfma_f32_16x16x32_bf16 v[72:75], v[178:181], v[204:207], v[72:75]
	v_mfma_f32_16x16x32_bf16 v[68:71], v[170:173], v[212:215], v[68:71]
	v_mfma_f32_16x16x32_bf16 v[64:67], v[178:181], v[212:215], v[64:67]
	v_mfma_f32_16x16x32_bf16 v[108:111], v[174:177], v[190:193], v[108:111]
	v_mfma_f32_16x16x32_bf16 v[104:107], v[182:185], v[190:193], v[104:107]
	v_mfma_f32_16x16x32_bf16 v[100:103], v[174:177], v[200:203], v[100:103]
	v_mfma_f32_16x16x32_bf16 v[96:99], v[182:185], v[200:203], v[96:99]
	v_mfma_f32_16x16x32_bf16 v[76:79], v[174:177], v[208:211], v[76:79]
	v_mfma_f32_16x16x32_bf16 v[72:75], v[182:185], v[208:211], v[72:75]
	v_mfma_f32_16x16x32_bf16 v[68:71], v[174:177], v[216:219], v[68:71]
	v_mfma_f32_16x16x32_bf16 v[64:67], v[182:185], v[216:219], v[64:67]
	s_setprio 0
	s_barrier
; #define PG8_STAGE(bufoff, gbase, voff) do { _Pragma("unroll") for (int _i = 0; _i < 2; ++_i) \
;         __builtin_amdgcn_global_load_lds((const unsigned*)((const char*)(gbase) + (voff)[_i]), (PG8_LAS unsigned*)(lds + (bufoff) + ldsw + _i * 8192), 16, 0, 0); } while (0)
; #define PG8_LDA(dst, b, h) do { _Pragma("unroll") for (int m = 0; m < 4; ++m) _Pragma("unroll") for (int k = 0; k < 2; ++k) dst[m][k] = *(const PG8_LAS bf16x8*)(lds + PG8_SA(b, h) + aoff + m * 2048 + k * 1024); } while (0)
; #define PG8_WAIT_V(n) asm volatile("s_waitcnt vmcnt(" #n ")" ::: "memory")
; #define PG8_WAIT_L(n) asm volatile("s_waitcnt lgkmcnt(" #n ")" ::: "memory")
; #define PG8_BAR __builtin_amdgcn_s_barrier()
; #define PG8_SCHED __builtin_amdgcn_sched_barrier(0)
; template <class Epi, class Sched, bool ALIGN_EPI = false, bool SP2 = false>
; __device__ __forceinline__ void gemm_phase(PG8_LAS unsigned char* lds, const Gemm g, const Sched& S, const Epi& E) {
;     ...
;             PG8_LDA(At, 1, 1); PG8_STAGE(PG8_SB(1, 0), b3, voffB); PG8_STAGE(PG8_SB(1, 1), b3 + hstep, voffB); PG8_STAGE(PG8_SA(1, 0), a3, voffA);
;             PG8_WAIT_V(8); PG8_WAIT_L(0); PG8_BAR; PG8_MMA(1, 0, At, B0); PG8_MMA(1, 1, At, B1); PG8_BAR; PG8_SCHED;
;     ...
;         if (!has_next) break;
; #pragma unroll
;         for (int a = 0; a < 2; ++a)
; #pragma unroll
;             for (int b = 0; b < 2; ++b)
; #pragma unroll
;                 for (int m = 0; m < 4; ++m)
; #pragma unroll
;                     for (int n = 0; n < 2; ++n) acc[a][b][m][n] = (f32x4){0.f, 0.f, 0.f, 0.f};
;         cur = nxt; cA = nA; cB = nB; ++ui;
	s_add_i32 s38, s71, s55
	v_lshl_add_u64 v[142:143], v[142:143], 0, s[20:21]
	s_mov_b32 m0, s38
	ds_read_b128 v[186:189], v141 offset:49152
	ds_read_b128 v[190:193], v141 offset:50176
	ds_read_b128 v[196:199], v141 offset:51200
	ds_read_b128 v[200:203], v141 offset:52224
	ds_read_b128 v[204:207], v141 offset:53248
	ds_read_b128 v[208:211], v141 offset:54272
	ds_read_b128 v[212:215], v141 offset:55296
	ds_read_b128 v[216:219], v141 offset:56320
	global_load_lds_dwordx4 v[142:143], off
	s_add_i32 m0, s38, 0x2000
	s_add_u32 s36, s36, 0xb0080
	v_lshl_add_u64 v[142:143], v[220:221], 0, s[20:21]
	s_addc_u32 s37, s37, 0
	s_add_i32 s38, s72, s55
	global_load_lds_dwordx4 v[142:143], off
	v_lshl_add_u64 v[142:143], s[36:37], 0, v[144:145]
	s_mov_b32 m0, s38
	s_nop 0
	global_load_lds_dwordx4 v[142:143], off
	v_lshl_add_u64 v[142:143], s[36:37], 0, v[128:129]
	s_add_i32 m0, s38, 0x2000
	s_nop 0
	global_load_lds_dwordx4 v[142:143], off
	v_lshl_add_u64 v[142:143], v[222:223], 0, s[20:21]
	s_mov_b32 m0, s64
	s_nop 0
	global_load_lds_dwordx4 v[142:143], off
	v_lshl_add_u64 v[142:143], v[224:225], 0, s[20:21]
	s_mov_b32 m0, s65
	s_nop 0
	global_load_lds_dwordx4 v[142:143], off
	s_waitcnt vmcnt(8)
	s_waitcnt lgkmcnt(0)
	s_barrier
	s_setprio 1
	s_waitcnt lgkmcnt(0)
	v_mfma_f32_16x16x32_bf16 v[60:63], v[150:153], v[186:189], v[60:63]
	v_mfma_f32_16x16x32_bf16 v[56:59], v[162:165], v[186:189], v[56:59]
	v_mfma_f32_16x16x32_bf16 v[52:55], v[150:153], v[196:199], v[52:55]
	v_mfma_f32_16x16x32_bf16 v[48:51], v[162:165], v[196:199], v[48:51]
	v_mfma_f32_16x16x32_bf16 v[28:31], v[150:153], v[204:207], v[28:31]
	v_mfma_f32_16x16x32_bf16 v[24:27], v[162:165], v[204:207], v[24:27]
	v_mfma_f32_16x16x32_bf16 v[20:23], v[150:153], v[212:215], v[20:23]
	v_mfma_f32_16x16x32_bf16 v[16:19], v[162:165], v[212:215], v[16:19]
	v_mfma_f32_16x16x32_bf16 v[60:63], v[158:161], v[190:193], v[60:63]
	v_mfma_f32_16x16x32_bf16 v[56:59], v[166:169], v[190:193], v[56:59]
	v_mfma_f32_16x16x32_bf16 v[52:55], v[158:161], v[200:203], v[52:55]
	v_mfma_f32_16x16x32_bf16 v[48:51], v[166:169], v[200:203], v[48:51]
	v_mfma_f32_16x16x32_bf16 v[28:31], v[158:161], v[208:211], v[28:31]
	v_mfma_f32_16x16x32_bf16 v[24:27], v[166:169], v[208:211], v[24:27]
	v_mfma_f32_16x16x32_bf16 v[20:23], v[158:161], v[216:219], v[20:23]
	v_mfma_f32_16x16x32_bf16 v[16:19], v[166:169], v[216:219], v[16:19]
	s_setprio 0
	s_setprio 1
	v_mfma_f32_16x16x32_bf16 v[44:47], v[170:173], v[186:189], v[44:47]
	v_mfma_f32_16x16x32_bf16 v[40:43], v[178:181], v[186:189], v[40:43]
	v_mfma_f32_16x16x32_bf16 v[36:39], v[170:173], v[196:199], v[36:39]
	v_mfma_f32_16x16x32_bf16 v[32:35], v[178:181], v[196:199], v[32:35]
	v_mfma_f32_16x16x32_bf16 v[12:15], v[170:173], v[204:207], v[12:15]
	v_mfma_f32_16x16x32_bf16 v[8:11], v[178:181], v[204:207], v[8:11]
	v_mfma_f32_16x16x32_bf16 v[4:7], v[170:173], v[212:215], v[4:7]
	v_mfma_f32_16x16x32_bf16 v[0:3], v[178:181], v[212:215], v[0:3]
	v_mfma_f32_16x16x32_bf16 v[44:47], v[174:177], v[190:193], v[44:47]
	v_mfma_f32_16x16x32_bf16 v[40:43], v[182:185], v[190:193], v[40:43]
	v_mfma_f32_16x16x32_bf16 v[36:39], v[174:177], v[200:203], v[36:39]
	v_mfma_f32_16x16x32_bf16 v[32:35], v[182:185], v[200:203], v[32:35]
	v_mfma_f32_16x16x32_bf16 v[12:15], v[174:177], v[208:211], v[12:15]
	v_mfma_f32_16x16x32_bf16 v[8:11], v[182:185], v[208:211], v[8:11]
	v_mfma_f32_16x16x32_bf16 v[4:7], v[174:177], v[216:219], v[4:7]
	v_mfma_f32_16x16x32_bf16 v[0:3], v[182:185], v[216:219], v[0:3]
	s_setprio 0
	s_add_i32 s70, s70, 2
	s_add_u32 s34, s34, 0x100
	s_addc_u32 s35, s35, 0
	s_cmp_gt_u32 s70, 41
	s_barrier
	s_cbranch_scc0 .LBB0_1134
	s_add_u32 s34, s29, 0xffffff00
	s_addc_u32 s35, s69, -1
	s_and_b64 vcc, exec, s[6:7]
	s_cbranch_vccnz .LBB0_1121
	v_mov_b32_e32 v0, 0
	s_mov_b32 s24, s67
	s_mov_b32 s53, s68
	s_mov_b64 s[26:27], s[30:31]
	s_mov_b32 s66, s28
	v_mov_b32_e32 v1, v0
	v_mov_b32_e32 v2, v0
	v_mov_b32_e32 v3, v0
	v_mov_b32_e32 v4, v0
	v_mov_b32_e32 v5, v0
	v_mov_b32_e32 v6, v0
	v_mov_b32_e32 v7, v0
	v_mov_b32_e32 v8, v0
	v_mov_b32_e32 v9, v0
	v_mov_b32_e32 v10, v0
	v_mov_b32_e32 v11, v0
	v_mov_b32_e32 v12, v0
	v_mov_b32_e32 v13, v0
	v_mov_b32_e32 v14, v0
	v_mov_b32_e32 v15, v0
	v_mov_b32_e32 v32, v0
	v_mov_b32_e32 v33, v0
	v_mov_b32_e32 v34, v0
	v_mov_b32_e32 v35, v0
	v_mov_b32_e32 v36, v0
	v_mov_b32_e32 v37, v0
	v_mov_b32_e32 v38, v0
	v_mov_b32_e32 v39, v0
	v_mov_b32_e32 v40, v0
	v_mov_b32_e32 v41, v0
	v_mov_b32_e32 v42, v0
	v_mov_b32_e32 v43, v0
	v_mov_b32_e32 v44, v0
	v_mov_b32_e32 v45, v0
	v_mov_b32_e32 v46, v0
	v_mov_b32_e32 v47, v0
	v_mov_b32_e32 v16, v0
	v_mov_b32_e32 v17, v0
	v_mov_b32_e32 v18, v0
	v_mov_b32_e32 v19, v0
	v_mov_b32_e32 v20, v0
	v_mov_b32_e32 v21, v0
	v_mov_b32_e32 v22, v0
	v_mov_b32_e32 v23, v0
	v_mov_b32_e32 v24, v0
	v_mov_b32_e32 v25, v0
	v_mov_b32_e32 v26, v0
	v_mov_b32_e32 v27, v0
	v_mov_b32_e32 v28, v0
	v_mov_b32_e32 v29, v0
	v_mov_b32_e32 v30, v0
	v_mov_b32_e32 v31, v0
	v_mov_b32_e32 v48, v0
	v_mov_b32_e32 v49, v0
	v_mov_b32_e32 v50, v0
	v_mov_b32_e32 v51, v0
	v_mov_b32_e32 v52, v0
	v_mov_b32_e32 v53, v0
	v_mov_b32_e32 v54, v0
	v_mov_b32_e32 v55, v0
	v_mov_b32_e32 v56, v0
	v_mov_b32_e32 v57, v0
	v_mov_b32_e32 v58, v0
	v_mov_b32_e32 v59, v0
	v_mov_b32_e32 v60, v0
	v_mov_b32_e32 v61, v0
	v_mov_b32_e32 v62, v0
	v_mov_b32_e32 v63, v0
	v_mov_b32_e32 v64, v0
	v_mov_b32_e32 v65, v0
	v_mov_b32_e32 v66, v0
	v_mov_b32_e32 v67, v0
	v_mov_b32_e32 v68, v0
	v_mov_b32_e32 v69, v0
	v_mov_b32_e32 v70, v0
	v_mov_b32_e32 v71, v0
	v_mov_b32_e32 v72, v0
	v_mov_b32_e32 v73, v0
	v_mov_b32_e32 v74, v0
	v_mov_b32_e32 v75, v0
	v_mov_b32_e32 v76, v0
	v_mov_b32_e32 v77, v0
	v_mov_b32_e32 v78, v0
	v_mov_b32_e32 v79, v0
	v_mov_b32_e32 v96, v0
	v_mov_b32_e32 v97, v0
	v_mov_b32_e32 v98, v0
	v_mov_b32_e32 v99, v0
	v_mov_b32_e32 v100, v0
	v_mov_b32_e32 v101, v0
	v_mov_b32_e32 v102, v0
	v_mov_b32_e32 v103, v0
	v_mov_b32_e32 v104, v0
	v_mov_b32_e32 v105, v0
	v_mov_b32_e32 v106, v0
	v_mov_b32_e32 v107, v0
	v_mov_b32_e32 v108, v0
	v_mov_b32_e32 v109, v0
	v_mov_b32_e32 v110, v0
	v_mov_b32_e32 v111, v0
	v_mov_b32_e32 v80, v0
	v_mov_b32_e32 v81, v0
	v_mov_b32_e32 v82, v0
	v_mov_b32_e32 v83, v0
	v_mov_b32_e32 v84, v0
	v_mov_b32_e32 v85, v0
	v_mov_b32_e32 v86, v0
	v_mov_b32_e32 v87, v0
	v_mov_b32_e32 v88, v0
	v_mov_b32_e32 v89, v0
	v_mov_b32_e32 v90, v0
	v_mov_b32_e32 v91, v0
	v_mov_b32_e32 v92, v0
	v_mov_b32_e32 v93, v0
	v_mov_b32_e32 v94, v0
	v_mov_b32_e32 v95, v0
	v_mov_b32_e32 v112, v0
	v_mov_b32_e32 v113, v0
	v_mov_b32_e32 v114, v0
	v_mov_b32_e32 v115, v0
	v_mov_b32_e32 v116, v0
	v_mov_b32_e32 v117, v0
	v_mov_b32_e32 v118, v0
	v_mov_b32_e32 v119, v0
	v_mov_b32_e32 v120, v0
	v_mov_b32_e32 v121, v0
	v_mov_b32_e32 v122, v0
	v_mov_b32_e32 v123, v0
	v_mov_b32_e32 v124, v0
	v_mov_b32_e32 v125, v0
	v_mov_b32_e32 v126, v0
	v_mov_b32_e32 v127, v0
	s_andn2_b64 vcc, exec, s[10:11]
	s_cbranch_vccnz .LBB0_1122
